# P0 window-row copy: 4 pieces in flight per thread (on top of attention restructure)
# speedup vs baseline: 1.0058x; 1.0058x over previous
; __device__ __forceinline__ void p0_prologue(const P& p, Frame& F) {
;     ...
;     { float* wsO = p.out + O_WS; const float* cw = p.in[I_CWIN];
;       for (int i = gt; i < BS * 508 * 128; i += NGT) { const int b = i / (508 * 128), r = i % (508 * 128); *(f32x4*)(wsO + (size_t)b * 512 * 512 + (size_t)r * 4) = *(const f32x4*)(cw + (size_t)b * 512 * 512 + 4 * 512 + (size_t)r * 4); } }
.LBB0_287:
	s_or_b64 exec, exec, s[4:5]
	s_mov_b32 s0, 0x1fc000
	v_cmp_gt_i32_e32 vcc, s0, v2
	s_and_saveexec_b64 s[0:1], vcc
	s_cbranch_execz .LBB0_290
	v_readlane_b32 s16, v253, 44
	v_readlane_b32 s17, v253, 45
	s_mov_b32 s2, 0x81020409
	s_add_u32 s18, s66, 0x2000
	s_addc_u32 s19, s67, 0
	s_add_u32 s4, s16, 0xc980000
	s_addc_u32 s5, s17, 0
	s_lshl_b32 s3, s76, 2
	s_mov_b32 s16, 0x1fc000
.Lp0win_trip:
	v_mov_b32_e32 v10, v2
	v_cmp_gt_i32_e64 s[8:9], s16, v10
	v_mul_hi_i32 v11, v10, s2
	v_add_u32_e32 v11, v11, v10
	v_lshrrev_b32_e32 v12, 31, v11
	v_ashrrev_i32_e32 v11, 15, v11
	v_add_u32_e32 v12, v11, v12
	v_mul_i32_i24_e32 v11, 0xfe00, v12
	v_sub_u32_e32 v11, v10, v11
	v_lshlrev_b32_e32 v12, 20, v12
	v_lshl_add_u32 v13, v11, 4, v12
	v_add_u32_e32 v14, s76, v10
	v_cmp_gt_i32_e64 s[10:11], s16, v14
	v_mul_hi_i32 v15, v14, s2
	v_add_u32_e32 v15, v15, v14
	v_lshrrev_b32_e32 v16, 31, v15
	v_ashrrev_i32_e32 v15, 15, v15
	v_add_u32_e32 v16, v15, v16
	v_mul_i32_i24_e32 v15, 0xfe00, v16
	v_sub_u32_e32 v15, v14, v15
	v_lshlrev_b32_e32 v16, 20, v16
	v_lshl_add_u32 v17, v15, 4, v16
	v_add_u32_e32 v18, s76, v14
	v_cmp_gt_i32_e64 s[12:13], s16, v18
	v_mul_hi_i32 v19, v18, s2
	v_add_u32_e32 v19, v19, v18
	v_lshrrev_b32_e32 v20, 31, v19
	v_ashrrev_i32_e32 v19, 15, v19
	v_add_u32_e32 v20, v19, v20
	v_mul_i32_i24_e32 v19, 0xfe00, v20
	v_sub_u32_e32 v19, v18, v19
	v_lshlrev_b32_e32 v20, 20, v20
	v_lshl_add_u32 v21, v19, 4, v20
	v_add_u32_e32 v22, s76, v18
	v_cmp_gt_i32_e64 s[14:15], s16, v22
	v_mul_hi_i32 v23, v22, s2
	v_add_u32_e32 v23, v23, v22
	v_lshrrev_b32_e32 v24, 31, v23
	v_ashrrev_i32_e32 v23, 15, v23
	v_add_u32_e32 v24, v23, v24
	v_mul_i32_i24_e32 v23, 0xfe00, v24
	v_sub_u32_e32 v23, v22, v23
	v_lshlrev_b32_e32 v24, 20, v24
	v_lshl_add_u32 v25, v23, 4, v24
	s_mov_b64 s[6:7], exec
	s_and_b64 exec, s[6:7], s[8:9]
	global_load_dwordx4 v[30:33], v13, s[18:19]
	s_and_b64 exec, s[6:7], s[10:11]
	global_load_dwordx4 v[34:37], v17, s[18:19]
	s_and_b64 exec, s[6:7], s[12:13]
	global_load_dwordx4 v[38:41], v21, s[18:19]
	s_and_b64 exec, s[6:7], s[14:15]
	global_load_dwordx4 v[42:45], v25, s[18:19]
	s_waitcnt vmcnt(0)
	s_and_b64 exec, s[6:7], s[8:9]
	global_store_dwordx4 v13, v[30:33], s[4:5]
	s_and_b64 exec, s[6:7], s[10:11]
	global_store_dwordx4 v17, v[34:37], s[4:5]
	s_and_b64 exec, s[6:7], s[12:13]
	global_store_dwordx4 v21, v[38:41], s[4:5]
	s_and_b64 exec, s[6:7], s[14:15]
	global_store_dwordx4 v25, v[42:45], s[4:5]
	s_mov_b64 exec, s[6:7]
	v_add_u32_e32 v2, s3, v2
	v_cmp_gt_i32_e32 vcc, 0x1fc000, v2
	s_and_b64 exec, exec, vcc
	s_cbranch_execnz .Lp0win_trip
